# pair8r with the P3 per-row s_barrier moved from the loop top to just after the first group of loads is issued
# baseline (speedup 1.0000x reference)
;     __device__ __forceinline__ unsigned a(const pg8::Unit& u) const { return (unsigned)u.pm * (256u * K * 2u); }
;     __device__ __forceinline__ unsigned a(const pg8::Unit& u) const { return (unsigned)u.pm * (256u * K * 2u); }
;     __device__ __forceinline__ unsigned a(const pg8::Unit& u) const { return (unsigned)u.pm * (256u * K * 2u); }
;     __device__ __forceinline__ unsigned a(const pg8::Unit& u) const { return (unsigned)u.pm * (256u * K * 2u); }
;     __device__ __forceinline__ unsigned a(const pg8::Unit& u) const { return (unsigned)u.pm * (256u * K * 2u); }
; __device__ __forceinline__ void p3_combine(const Frame& F) {
;     ...
;     for (int m = gw; m < M; m += NGW) {
; #pragma unroll
;         for (int j = 0; j < 4; ++j) {
;             const int col = j * 512 + lane * 8, head = col >> 7; const size_t e = (size_t)m * EB + col;
;             const int sq = m >> 13, pos = m & (SEQ - 1);
;             const float l0 = F.LSE[((size_t)(0 * 16 + head) * NSEQ + sq) * SEQ + pos], l1 = F.LSE[((size_t)(1 * 16 + head) * NSEQ + sq) * SEQ + ((pos & 3) << 11) + (pos >> 2)],
;                         l2 = F.LSE[((size_t)(2 * 16 + head) * NSEQ + sq) * SEQ + ((pos & 15) << 9) + (pos >> 4)];
;             const float mx = fmaxf(l0, fmaxf(l1, l2));
;             float e0 = __builtin_amdgcn_exp2f(l0 - mx), e1 = __builtin_amdgcn_exp2f(l1 - mx), e2 = __builtin_amdgcn_exp2f(l2 - mx);
;             const float inv = 1.f / (e0 + e1 + e2); e0 *= inv; e1 *= inv; e2 *= inv;
;             const u32x2 a = *(const u32x2*)((const unsigned char*)F.OG0 + e), b = *(const u32x2*)((const unsigned char*)F.OG1 + e), c = *(const u32x2*)((const unsigned char*)F.OG2 + e);
;             const u32x4 z = *(const u32x4*)(F.ZB + e);
;             const unsigned aw[2] = {a.x, a.y}, bw[2] = {b.x, b.y}, cw[2] = {c.x, c.y}, zw[4] = {z.x, z.y, z.z, z.w};
.LBB0_365:
	v_lshl_add_u64 v[36:37], s[18:19], 0, v[4:5]
	v_add_co_u32_e32 v44, vcc, s7, v36
	s_ashr_i32 s64, s6, 13
	s_nop 0
	v_addc_co_u32_e32 v45, vcc, 0, v37, vcc
	v_add_co_u32_e32 v46, vcc, s9, v36
	v_lshl_add_u64 v[42:43], s[24:25], 0, v[4:5]
	s_nop 0
	v_addc_co_u32_e32 v47, vcc, 0, v37, vcc
	v_add_co_u32_e32 v48, vcc, s11, v36
	s_ashr_i32 s65, s64, 31
	s_nop 0
	v_addc_co_u32_e32 v49, vcc, 0, v37, vcc
	v_add_co_u32_e32 v36, vcc, s33, v42
	global_load_dwordx4 v[0:3], v[30:31], off offset:-3072
	s_nop 0
	v_addc_co_u32_e32 v37, vcc, 0, v43, vcc
	v_lshl_add_u64 v[42:43], s[64:65], 0, v[6:7]
	v_lshl_add_u64 v[50:51], s[64:65], 0, v[8:9]
	v_lshl_add_u64 v[52:53], s[64:65], 0, v[10:11]
	s_and_b32 s35, s6, 0x1fff
	s_and_b32 s58, s3, 0x1800
	s_and_b32 s62, s0, 0x1e00
	global_load_dwordx2 v[54:55], v[44:45], off
	global_load_dwordx2 v[56:57], v[46:47], off
	global_load_dwordx2 v[58:59], v[48:49], off
	v_lshl_add_u64 v[72:73], s[64:65], 0, v[24:25]
	v_lshl_add_u64 v[74:75], s[64:65], 0, v[26:27]
	v_lshl_add_u64 v[76:77], s[64:65], 0, v[28:29]
	v_lshlrev_b64 v[42:43], 15, v[42:43]
	v_lshlrev_b64 v[50:51], 15, v[50:51]
	v_lshlrev_b64 v[52:53], 15, v[52:53]
	s_lshr_b32 s60, s6, 2
	s_mov_b32 s57, s51
	s_mov_b32 s59, s51
	s_mov_b32 s63, s51
	s_lshl_b32 s56, s35, 2
	s_lshl_b32 s58, s58, 2
	s_lshl_b32 s62, s62, 2
	v_lshlrev_b64 v[72:73], 15, v[72:73]
	v_lshlrev_b64 v[74:75], 15, v[74:75]
	v_lshlrev_b64 v[76:77], 15, v[76:77]
	v_lshl_add_u64 v[42:43], s[54:55], 0, v[42:43]
	v_lshl_add_u64 v[50:51], s[54:55], 0, v[50:51]
	v_lshl_add_u64 v[52:53], s[54:55], 0, v[52:53]
	s_and_b32 s50, s6, 0x1ffc
	s_mov_b32 s61, s51
	s_and_b32 s60, s60, 0x7fc
	v_lshl_add_u64 v[72:73], s[54:55], 0, v[72:73]
	v_lshl_add_u64 v[74:75], s[54:55], 0, v[74:75]
	v_lshl_add_u64 v[76:77], s[54:55], 0, v[76:77]
	v_lshl_add_u64 v[78:79], v[42:43], 0, s[56:57]
	v_lshl_add_u64 v[50:51], v[50:51], 0, s[58:59]
	v_lshl_add_u64 v[52:53], v[52:53], 0, s[62:63]
	v_lshl_add_u64 v[42:43], v[72:73], 0, s[56:57]
	v_lshl_add_u64 v[72:73], v[74:75], 0, s[58:59]
	v_lshl_add_u64 v[74:75], v[76:77], 0, s[62:63]
	v_lshl_add_u64 v[76:77], v[50:51], 0, s[50:51]
	v_lshl_add_u64 v[80:81], v[52:53], 0, s[60:61]
	global_load_dword v87, v[78:79], off
	global_load_dword v90, v[76:77], off
	global_load_dword v91, v[80:81], off
	v_lshl_add_u64 v[52:53], v[74:75], 0, s[60:61]
	v_lshl_add_u64 v[50:51], v[72:73], 0, s[50:51]
	v_lshl_add_u64 v[60:61], s[64:65], 0, v[12:13]
	v_lshl_add_u64 v[66:67], s[64:65], 0, v[18:19]
	v_lshlrev_b64 v[60:61], 15, v[60:61]
	v_lshlrev_b64 v[66:67], 15, v[66:67]
	v_lshl_add_u64 v[60:61], s[54:55], 0, v[60:61]
	v_lshl_add_u64 v[66:67], s[54:55], 0, v[66:67]
	v_lshl_add_u64 v[60:61], v[60:61], 0, s[56:57]
	v_lshl_add_u64 v[66:67], v[66:67], 0, s[56:57]
	v_mov_b32_e32 v32, 0
	v_mov_b32_e32 v33, 0
	v_lshl_add_u64 v[62:63], s[64:65], 0, v[14:15]
	v_lshl_add_u64 v[64:65], s[64:65], 0, v[16:17]
	v_lshlrev_b64 v[62:63], 15, v[62:63]
	v_lshlrev_b64 v[64:65], 15, v[64:65]
	v_lshl_add_u64 v[62:63], s[54:55], 0, v[62:63]
	v_lshl_add_u64 v[64:65], s[54:55], 0, v[64:65]
	v_lshl_add_u64 v[62:63], v[62:63], 0, s[58:59]
	v_lshl_add_u64 v[64:65], v[64:65], 0, s[62:63]
	v_lshl_add_u64 v[62:63], v[62:63], 0, s[50:51]
	v_lshl_add_u64 v[64:65], v[64:65], 0, s[60:61]
	v_mov_b32_e32 v34, 0
	v_mov_b32_e32 v35, 0
	v_lshl_add_u64 v[68:69], s[64:65], 0, v[20:21]
	v_lshl_add_u64 v[70:71], s[64:65], 0, v[22:23]
	v_lshlrev_b64 v[68:69], 15, v[68:69]
	v_lshlrev_b64 v[70:71], 15, v[70:71]
	v_lshl_add_u64 v[68:69], s[54:55], 0, v[68:69]
	v_lshl_add_u64 v[70:71], s[54:55], 0, v[70:71]
	v_lshl_add_u64 v[68:69], v[68:69], 0, s[58:59]
	v_lshl_add_u64 v[70:71], v[70:71], 0, s[62:63]
	v_lshl_add_u64 v[68:69], v[68:69], 0, s[50:51]
	v_lshl_add_u64 v[70:71], v[70:71], 0, s[60:61]
	v_mov_b32_e32 v38, 0
	v_mov_b32_e32 v39, 0
	s_barrier
	s_waitcnt vmcnt(6)
	v_lshlrev_b32_e32 v92, 16, v0
	v_and_b32_e32 v93, 0xffff0000, v0
	v_lshlrev_b32_e32 v94, 16, v1
	v_and_b32_e32 v95, 0xffff0000, v1
	v_lshlrev_b32_e32 v96, 16, v2
	v_and_b32_e32 v97, 0xffff0000, v2
	v_lshlrev_b32_e32 v98, 16, v3
	s_waitcnt vmcnt(5)
	v_cvt_pk_f32_fp8_e32 v[0:1], v54
	v_cvt_pk_f32_fp8_sdwa v[74:75], v54 src0_sel:WORD_1
	v_cvt_pk_f32_fp8_e32 v[80:81], v55
	v_cvt_pk_f32_fp8_sdwa v[54:55], v55 src0_sel:WORD_1
	s_waitcnt vmcnt(3)
	v_cvt_pk_f32_fp8_e32 v[72:73], v58
	v_cvt_pk_f32_fp8_sdwa v[78:79], v58 src0_sel:WORD_1
	v_cvt_pk_f32_fp8_e32 v[84:85], v59
	v_cvt_pk_f32_fp8_sdwa v[58:59], v59 src0_sel:WORD_1
	v_mov_b32_e32 v88, v74
	v_mov_b32_e32 v74, v80
	v_mov_b32_e32 v80, v54
	v_mov_b32_e32 v89, v78
	v_mov_b32_e32 v78, v75
	v_mov_b32_e32 v75, v84
	v_mov_b32_e32 v84, v81
	v_mov_b32_e32 v81, v58
	v_mov_b32_e32 v58, v55
	v_and_b32_e32 v99, 0xffff0000, v3
	v_cvt_pk_f32_fp8_e32 v[2:3], v56
	v_cvt_pk_f32_fp8_sdwa v[76:77], v56 src0_sel:WORD_1
	v_cvt_pk_f32_fp8_e32 v[82:83], v57
	v_cvt_pk_f32_fp8_sdwa v[56:57], v57 src0_sel:WORD_1
	v_mov_b32_e32 v86, v72
	v_mov_b32_e32 v40, 0
	v_mov_b32_e32 v41, 0
	s_add_i32 s6, s6, s8
	s_add_i32 s0, s0, s1
	s_add_i32 s3, s3, s10
	s_add_u32 s18, s18, s20
	s_addc_u32 s19, s19, s21
	s_add_u32 s24, s24, s20
	s_addc_u32 s25, s25, s21
	s_cmpk_lt_i32 s6, 0x6000
	s_waitcnt vmcnt(0)
;     __device__ __forceinline__ unsigned a(const pg8::Unit& u) const { return (unsigned)u.pm * (256u * K * 2u); }
;     __device__ __forceinline__ unsigned a(const pg8::Unit& u) const { return (unsigned)u.pm * (256u * K * 2u); }
;     __device__ __forceinline__ unsigned a(const pg8::Unit& u) const { return (unsigned)u.pm * (256u * K * 2u); }
;     __device__ __forceinline__ unsigned a(const pg8::Unit& u) const { return (unsigned)u.pm * (256u * K * 2u); }
;     __device__ __forceinline__ unsigned a(const pg8::Unit& u) const { return (unsigned)u.pm * (256u * K * 2u); }
; __device__ __forceinline__ void p3_combine(const Frame& F) {
;     ...
;             const int col = j * 512 + lane * 8, head = col >> 7; const size_t e = (size_t)m * EB + col;
;             const int sq = m >> 13, pos = m & (SEQ - 1);
;             const float l0 = F.LSE[((size_t)(0 * 16 + head) * NSEQ + sq) * SEQ + pos], l1 = F.LSE[((size_t)(1 * 16 + head) * NSEQ + sq) * SEQ + ((pos & 3) << 11) + (pos >> 2)],
;                         l2 = F.LSE[((size_t)(2 * 16 + head) * NSEQ + sq) * SEQ + ((pos & 15) << 9) + (pos >> 4)];
;             const float mx = fmaxf(l0, fmaxf(l1, l2));
;             float e0 = __builtin_amdgcn_exp2f(l0 - mx), e1 = __builtin_amdgcn_exp2f(l1 - mx), e2 = __builtin_amdgcn_exp2f(l2 - mx);
;             const float inv = 1.f / (e0 + e1 + e2); e0 *= inv; e1 *= inv; e2 *= inv;
;             const u32x2 a = *(const u32x2*)((const unsigned char*)F.OG0 + e), b = *(const u32x2*)((const unsigned char*)F.OG1 + e), c = *(const u32x2*)((const unsigned char*)F.OG2 + e);
;             const u32x4 z = *(const u32x4*)(F.ZB + e);
;             const unsigned aw[2] = {a.x, a.y}, bw[2] = {b.x, b.y}, cw[2] = {c.x, c.y}, zw[4] = {z.x, z.y, z.z, z.w};
;             float ov[8];
;     ...
;             P3_PAIR(0, 0, false); P3_PAIR(1, 0, true); P3_PAIR(2, 1, false); P3_PAIR(3, 1, true);
;     ...
;             int lo8 = 0, hi8 = 0;
;             lo8 = __builtin_amdgcn_cvt_pk_fp8_f32(ov[0], ov[1], lo8, false); lo8 = __builtin_amdgcn_cvt_pk_fp8_f32(ov[2], ov[3], lo8, true);
;             hi8 = __builtin_amdgcn_cvt_pk_fp8_f32(ov[4], ov[5], hi8, false); hi8 = __builtin_amdgcn_cvt_pk_fp8_f32(ov[6], ov[7], hi8, true);
;             *(u32x2*)(F.OBZ8 + e) = (u32x2){(unsigned)lo8, (unsigned)hi8};
	v_max3_f32 v54, v87, v90, v91
	v_sub_f32_e32 v55, v87, v54
	v_sub_f32_e32 v87, v90, v54
	v_sub_f32_e32 v90, v91, v54
	v_exp_f32_e32 v54, v55
	v_exp_f32_e32 v87, v87
	v_exp_f32_e32 v55, v90
	v_add_f32_e32 v90, v54, v87
	v_add_f32_e32 v90, v55, v90
	v_div_scale_f32 v91, s[56:57], v90, v90, 1.0
	v_rcp_f32_e32 v101, v91
	v_div_scale_f32 v100, vcc, 1.0, v90, 1.0
	v_fma_f32 v102, -v91, v101, 1.0
	v_fmac_f32_e32 v101, v102, v101
	v_mul_f32_e32 v102, v100, v101
	v_fma_f32 v103, -v91, v102, v100
	v_fmac_f32_e32 v102, v103, v101
	v_fma_f32 v91, -v91, v102, v100
	v_div_fmas_f32 v91, v91, v101, v102
	v_div_fixup_f32 v90, v91, v90, 1.0
	v_pk_mul_f32 v[54:55], v[54:55], v[90:91] op_sel_hi:[1,0]
	v_mul_f32_e32 v100, v87, v90
	v_pk_mov_b32 v[90:91], v[54:55], v[0:1] op_sel:[1,0]
	v_mov_b32_e32 v87, v54
	v_mov_b32_e32 v0, v55
	v_pk_mov_b32 v[72:73], v[72:73], v[54:55] op_sel:[1,0]
	v_pk_mul_f32 v[88:89], v[54:55], v[88:89]
	v_pk_mul_f32 v[78:79], v[54:55], v[78:79]
	v_pk_mul_f32 v[74:75], v[54:55], v[74:75]
	v_pk_mul_f32 v[84:85], v[54:55], v[84:85]
	v_pk_mul_f32 v[80:81], v[54:55], v[80:81]
	v_pk_mul_f32 v[54:55], v[54:55], v[58:59]
	v_pk_mul_f32 v[58:59], v[90:91], v[86:87]
	v_pk_mul_f32 v[0:1], v[0:1], v[72:73]
	v_fma_f32 v72, v100, v76, v88
	v_fma_f32 v73, v100, v77, v78
	v_fma_f32 v74, v100, v82, v74
	v_fma_f32 v76, v100, v83, v84
	v_fma_f32 v2, v2, v100, v59
	v_fma_f32 v1, v3, v100, v1
	v_fma_f32 v54, v100, v57, v54
	v_add_f32_e32 v3, v72, v89
	v_add_f32_e32 v57, v73, v79
	v_add_f32_e32 v59, v74, v75
	v_add_f32_e32 v72, v76, v85
	v_add_f32_e32 v2, v58, v2
	v_add_f32_e32 v0, v0, v1
	v_add_f32_e32 v54, v54, v55
	v_mul_f32_e32 v1, v3, v94
	v_mul_f32_e32 v3, v57, v95
	v_mul_f32_e32 v55, v59, v96
	v_mul_f32_e32 v57, v72, v97
	v_mul_f32_e32 v2, v2, v92
	v_mul_f32_e32 v0, v0, v93
	v_add_f32_e32 v55, v55, v55
	v_add_f32_e32 v57, v57, v57
	v_add_f32_e32 v2, v2, v2
	v_add_f32_e32 v0, v0, v0
	v_fma_f32 v56, v100, v56, v80
	v_cvt_pk_fp8_f32 v33, v55, v57
	v_cvt_pk_fp8_f32 v32, v2, v0
	v_add_f32_e32 v56, v56, v81
	v_mul_f32_e32 v56, v56, v98
	v_mul_f32_e32 v54, v54, v99
	v_add_f32_e32 v1, v1, v1
	v_add_f32_e32 v3, v3, v3
	v_add_f32_e32 v56, v56, v56
	v_add_f32_e32 v54, v54, v54
	v_cvt_pk_fp8_f32 v33, v56, v54 op_sel:[0,0,1]
	v_cvt_pk_fp8_f32 v32, v1, v3 op_sel:[0,0,1]
	global_store_dwordx2 v[36:37], v[32:33], off
	global_load_dword v80, v[60:61], off
	global_load_dword v81, v[62:63], off
	global_load_dword v82, v[64:65], off
	s_nop 0
	global_load_dwordx2 v[32:33], v[44:45], off offset:512
	global_load_dwordx2 v[54:55], v[46:47], off offset:512
	global_load_dwordx2 v[56:57], v[48:49], off offset:512
	global_load_dwordx4 v[0:3], v[30:31], off offset:-2048
	s_waitcnt vmcnt(4)
	v_max3_f32 v83, v80, v81, v82
	s_waitcnt vmcnt(3)
	v_cvt_pk_f32_fp8_e32 v[58:59], v32
	v_cvt_pk_f32_fp8_sdwa v[64:65], v32 src0_sel:WORD_1
	s_waitcnt vmcnt(1)
	v_cvt_pk_f32_fp8_e32 v[62:63], v56
	s_waitcnt vmcnt(0)
	v_lshlrev_b32_e32 v88, 16, v2
	v_and_b32_e32 v89, 0xffff0000, v2
	v_lshlrev_b32_e32 v90, 16, v3
	v_and_b32_e32 v91, 0xffff0000, v3
	v_sub_f32_e32 v2, v80, v83
	v_sub_f32_e32 v3, v81, v83
	v_lshlrev_b32_e32 v84, 16, v0
	v_and_b32_e32 v85, 0xffff0000, v0
	v_lshlrev_b32_e32 v86, 16, v1
	v_and_b32_e32 v87, 0xffff0000, v1
	v_cvt_pk_f32_fp8_e32 v[0:1], v33
	v_cvt_pk_f32_fp8_sdwa v[32:33], v33 src0_sel:WORD_1
	v_sub_f32_e32 v80, v82, v83
	v_exp_f32_e32 v2, v2
	v_exp_f32_e32 v81, v3
	v_exp_f32_e32 v3, v80
	v_cvt_pk_f32_fp8_sdwa v[74:75], v56 src0_sel:WORD_1
	v_cvt_pk_f32_fp8_e32 v[78:79], v57
	v_cvt_pk_f32_fp8_sdwa v[56:57], v57 src0_sel:WORD_1
	v_mov_b32_e32 v82, v64
	v_mov_b32_e32 v64, v0
	v_mov_b32_e32 v0, v32
	v_add_f32_e32 v32, v2, v81
	v_add_f32_e32 v32, v3, v32
	v_mov_b32_e32 v83, v74
	v_mov_b32_e32 v74, v65
	v_mov_b32_e32 v65, v78
	v_mov_b32_e32 v78, v1
	v_mov_b32_e32 v1, v56
	v_mov_b32_e32 v56, v33
	v_div_scale_f32 v33, s[56:57], v32, v32, 1.0
	v_rcp_f32_e32 v93, v33
	v_div_scale_f32 v92, vcc, 1.0, v32, 1.0
	v_cvt_pk_f32_fp8_e32 v[60:61], v54
	v_fma_f32 v94, -v33, v93, 1.0
	v_fmac_f32_e32 v93, v94, v93
	v_mul_f32_e32 v94, v92, v93
	v_fma_f32 v95, -v33, v94, v92
	v_fmac_f32_e32 v94, v95, v93
	v_fma_f32 v33, -v33, v94, v92
	v_div_fmas_f32 v33, v33, v93, v94
	v_cvt_pk_f32_fp8_sdwa v[72:73], v54 src0_sel:WORD_1
	v_cvt_pk_f32_fp8_e32 v[76:77], v55
	v_cvt_pk_f32_fp8_sdwa v[54:55], v55 src0_sel:WORD_1
	v_div_fixup_f32 v32, v33, v32, 1.0
	v_pk_mul_f32 v[2:3], v[2:3], v[32:33] op_sel_hi:[1,0]
	v_mov_b32_e32 v80, v62
	v_mul_f32_e32 v92, v81, v32
	v_pk_mov_b32 v[32:33], v[2:3], v[58:59] op_sel:[1,0]
	v_mov_b32_e32 v81, v2
	v_mov_b32_e32 v58, v3
	v_pk_mov_b32 v[62:63], v[62:63], v[2:3] op_sel:[1,0]
	v_pk_mul_f32 v[82:83], v[2:3], v[82:83]
	v_pk_mul_f32 v[74:75], v[2:3], v[74:75]
	v_pk_mul_f32 v[64:65], v[2:3], v[64:65]
	v_pk_mul_f32 v[78:79], v[2:3], v[78:79]
	v_pk_mul_f32 v[0:1], v[2:3], v[0:1]
	v_pk_mul_f32 v[2:3], v[2:3], v[56:57]
	v_pk_mul_f32 v[32:33], v[32:33], v[80:81]
	v_pk_mul_f32 v[56:57], v[58:59], v[62:63]
	v_fma_f32 v58, v92, v72, v82
	v_fma_f32 v59, v92, v73, v74
	v_fma_f32 v62, v92, v76, v64
	v_fma_f32 v63, v92, v77, v78
	v_fma_f32 v0, v92, v54, v0
	v_fma_f32 v2, v92, v55, v2
	v_fma_f32 v33, v60, v92, v33
	v_fma_f32 v54, v61, v92, v57
	v_add_f32_e32 v55, v58, v83
	v_add_f32_e32 v57, v59, v75
	v_add_f32_e32 v58, v62, v65
	v_add_f32_e32 v59, v63, v79
	v_add_f32_e32 v0, v0, v1
	v_add_f32_e32 v1, v2, v3
	v_add_f32_e32 v2, v32, v33
	v_add_f32_e32 v3, v56, v54
	v_mul_f32_e32 v32, v55, v86
	v_mul_f32_e32 v54, v58, v88
	v_mul_f32_e32 v55, v59, v89
	v_mul_f32_e32 v2, v2, v84
	v_mul_f32_e32 v3, v3, v85
	v_add_f32_e32 v54, v54, v54
	v_add_f32_e32 v55, v55, v55
	v_add_f32_e32 v2, v2, v2
	v_add_f32_e32 v3, v3, v3
	v_cvt_pk_fp8_f32 v35, v54, v55
	v_cvt_pk_fp8_f32 v34, v2, v3
	v_mul_f32_e32 v33, v57, v87
	v_mul_f32_e32 v0, v0, v90
	v_mul_f32_e32 v1, v1, v91
	v_add_f32_e32 v32, v32, v32
	v_add_f32_e32 v33, v33, v33
	v_add_f32_e32 v0, v0, v0
	v_add_f32_e32 v1, v1, v1
	v_cvt_pk_fp8_f32 v35, v0, v1 op_sel:[0,0,1]
	v_cvt_pk_fp8_f32 v34, v32, v33 op_sel:[0,0,1]
	global_store_dwordx2 v[36:37], v[34:35], off offset:512
	global_load_dword v72, v[66:67], off
	global_load_dword v73, v[68:69], off
	global_load_dword v74, v[70:71], off
	global_load_dwordx2 v[32:33], v[44:45], off offset:1024
	s_nop 0
	global_load_dwordx2 v[34:35], v[46:47], off offset:1024
	global_load_dwordx2 v[54:55], v[48:49], off offset:1024
	global_load_dwordx4 v[0:3], v[30:31], off offset:-1024
	s_waitcnt vmcnt(4)
;     __device__ __forceinline__ unsigned a(const pg8::Unit& u) const { return (unsigned)u.pm * (256u * K * 2u); }
;     __device__ __forceinline__ unsigned a(const pg8::Unit& u) const { return (unsigned)u.pm * (256u * K * 2u); }
;     __device__ __forceinline__ unsigned a(const pg8::Unit& u) const { return (unsigned)u.pm * (256u * K * 2u); }
;     __device__ __forceinline__ unsigned a(const pg8::Unit& u) const { return (unsigned)u.pm * (256u * K * 2u); }
;     __device__ __forceinline__ unsigned a(const pg8::Unit& u) const { return (unsigned)u.pm * (256u * K * 2u); }
; __device__ __forceinline__ void p3_combine(const Frame& F) {
;     ...
;             const int col = j * 512 + lane * 8, head = col >> 7; const size_t e = (size_t)m * EB + col;
;             const int sq = m >> 13, pos = m & (SEQ - 1);
;             const float l0 = F.LSE[((size_t)(0 * 16 + head) * NSEQ + sq) * SEQ + pos], l1 = F.LSE[((size_t)(1 * 16 + head) * NSEQ + sq) * SEQ + ((pos & 3) << 11) + (pos >> 2)],
;                         l2 = F.LSE[((size_t)(2 * 16 + head) * NSEQ + sq) * SEQ + ((pos & 15) << 9) + (pos >> 4)];
;             const float mx = fmaxf(l0, fmaxf(l1, l2));
;             float e0 = __builtin_amdgcn_exp2f(l0 - mx), e1 = __builtin_amdgcn_exp2f(l1 - mx), e2 = __builtin_amdgcn_exp2f(l2 - mx);
;             const float inv = 1.f / (e0 + e1 + e2); e0 *= inv; e1 *= inv; e2 *= inv;
;             const u32x2 a = *(const u32x2*)((const unsigned char*)F.OG0 + e), b = *(const u32x2*)((const unsigned char*)F.OG1 + e), c = *(const u32x2*)((const unsigned char*)F.OG2 + e);
;             const u32x4 z = *(const u32x4*)(F.ZB + e);
;             const unsigned aw[2] = {a.x, a.y}, bw[2] = {b.x, b.y}, cw[2] = {c.x, c.y}, zw[4] = {z.x, z.y, z.z, z.w};
;             float ov[8];
;     ...
;             P3_PAIR(0, 0, false); P3_PAIR(1, 0, true); P3_PAIR(2, 1, false); P3_PAIR(3, 1, true);
;     ...
;             int lo8 = 0, hi8 = 0;
;             lo8 = __builtin_amdgcn_cvt_pk_fp8_f32(ov[0], ov[1], lo8, false); lo8 = __builtin_amdgcn_cvt_pk_fp8_f32(ov[2], ov[3], lo8, true);
;             hi8 = __builtin_amdgcn_cvt_pk_fp8_f32(ov[4], ov[5], hi8, false); hi8 = __builtin_amdgcn_cvt_pk_fp8_f32(ov[6], ov[7], hi8, true);
;             *(u32x2*)(F.OBZ8 + e) = (u32x2){(unsigned)lo8, (unsigned)hi8};
	v_max3_f32 v75, v72, v73, v74
	s_waitcnt vmcnt(3)
	v_cvt_pk_f32_fp8_e32 v[56:57], v32
	v_cvt_pk_f32_fp8_sdwa v[62:63], v32 src0_sel:WORD_1
	s_waitcnt vmcnt(1)
	v_cvt_pk_f32_fp8_e32 v[60:61], v54
	s_waitcnt vmcnt(0)
	v_lshlrev_b32_e32 v80, 16, v2
	v_and_b32_e32 v81, 0xffff0000, v2
	v_lshlrev_b32_e32 v82, 16, v3
	v_and_b32_e32 v83, 0xffff0000, v3
	v_sub_f32_e32 v2, v72, v75
	v_sub_f32_e32 v3, v73, v75
	v_lshlrev_b32_e32 v76, 16, v0
	v_and_b32_e32 v77, 0xffff0000, v0
	v_lshlrev_b32_e32 v78, 16, v1
	v_and_b32_e32 v79, 0xffff0000, v1
	v_cvt_pk_f32_fp8_e32 v[0:1], v33
	v_cvt_pk_f32_fp8_sdwa v[32:33], v33 src0_sel:WORD_1
	v_sub_f32_e32 v72, v74, v75
	v_exp_f32_e32 v2, v2
	v_exp_f32_e32 v73, v3
	v_exp_f32_e32 v3, v72
	v_cvt_pk_f32_fp8_sdwa v[66:67], v54 src0_sel:WORD_1
	v_cvt_pk_f32_fp8_e32 v[70:71], v55
	v_cvt_pk_f32_fp8_sdwa v[54:55], v55 src0_sel:WORD_1
	v_mov_b32_e32 v74, v62
	v_mov_b32_e32 v62, v0
	v_mov_b32_e32 v0, v32
	v_add_f32_e32 v32, v2, v73
	v_add_f32_e32 v32, v3, v32
	v_mov_b32_e32 v75, v66
	v_mov_b32_e32 v66, v63
	v_mov_b32_e32 v63, v70
	v_mov_b32_e32 v70, v1
	v_mov_b32_e32 v1, v54
	v_mov_b32_e32 v54, v33
	v_div_scale_f32 v33, s[56:57], v32, v32, 1.0
	v_rcp_f32_e32 v85, v33
	v_div_scale_f32 v84, vcc, 1.0, v32, 1.0
	v_cvt_pk_f32_fp8_e32 v[58:59], v34
	v_fma_f32 v86, -v33, v85, 1.0
	v_fmac_f32_e32 v85, v86, v85
	v_mul_f32_e32 v86, v84, v85
	v_fma_f32 v87, -v33, v86, v84
	v_fmac_f32_e32 v86, v87, v85
	v_fma_f32 v33, -v33, v86, v84
	v_div_fmas_f32 v33, v33, v85, v86
	v_cvt_pk_f32_fp8_sdwa v[64:65], v34 src0_sel:WORD_1
	v_cvt_pk_f32_fp8_e32 v[68:69], v35
	v_cvt_pk_f32_fp8_sdwa v[34:35], v35 src0_sel:WORD_1
	v_div_fixup_f32 v32, v33, v32, 1.0
	v_pk_mul_f32 v[2:3], v[2:3], v[32:33] op_sel_hi:[1,0]
	v_mov_b32_e32 v72, v60
	v_mul_f32_e32 v84, v73, v32
	v_pk_mov_b32 v[32:33], v[2:3], v[56:57] op_sel:[1,0]
	v_mov_b32_e32 v73, v2
	v_mov_b32_e32 v56, v3
	v_pk_mov_b32 v[60:61], v[60:61], v[2:3] op_sel:[1,0]
	v_pk_mul_f32 v[74:75], v[2:3], v[74:75]
	v_pk_mul_f32 v[66:67], v[2:3], v[66:67]
	v_pk_mul_f32 v[62:63], v[2:3], v[62:63]
	v_pk_mul_f32 v[70:71], v[2:3], v[70:71]
	v_pk_mul_f32 v[0:1], v[2:3], v[0:1]
	v_pk_mul_f32 v[2:3], v[2:3], v[54:55]
	v_pk_mul_f32 v[32:33], v[32:33], v[72:73]
	v_pk_mul_f32 v[54:55], v[56:57], v[60:61]
	v_fma_f32 v56, v84, v64, v74
	v_fma_f32 v57, v84, v65, v66
	v_fma_f32 v60, v84, v68, v62
	v_fma_f32 v61, v84, v69, v70
	v_fma_f32 v0, v84, v34, v0
	v_fma_f32 v2, v84, v35, v2
	v_fma_f32 v33, v58, v84, v33
	v_fma_f32 v34, v59, v84, v55
	v_add_f32_e32 v35, v56, v75
	v_add_f32_e32 v55, v57, v67
	v_add_f32_e32 v56, v60, v63
	v_add_f32_e32 v57, v61, v71
	v_add_f32_e32 v0, v0, v1
	v_add_f32_e32 v1, v2, v3
	v_add_f32_e32 v2, v32, v33
	v_add_f32_e32 v3, v54, v34
	v_mul_f32_e32 v32, v35, v78
	v_mul_f32_e32 v34, v56, v80
	v_mul_f32_e32 v35, v57, v81
	v_mul_f32_e32 v2, v2, v76
	v_mul_f32_e32 v3, v3, v77
	v_add_f32_e32 v34, v34, v34
	v_add_f32_e32 v35, v35, v35
	v_add_f32_e32 v2, v2, v2
	v_add_f32_e32 v3, v3, v3
	v_cvt_pk_fp8_f32 v39, v34, v35
	v_cvt_pk_fp8_f32 v38, v2, v3
	v_mul_f32_e32 v33, v55, v79
	v_mul_f32_e32 v0, v0, v82
	v_mul_f32_e32 v1, v1, v83
	v_add_f32_e32 v32, v32, v32
	v_add_f32_e32 v33, v33, v33
	v_add_f32_e32 v0, v0, v0
	v_add_f32_e32 v1, v1, v1
	v_cvt_pk_fp8_f32 v39, v0, v1 op_sel:[0,0,1]
	v_cvt_pk_fp8_f32 v38, v32, v33 op_sel:[0,0,1]
	global_store_dwordx2 v[36:37], v[38:39], off offset:1024
	global_load_dword v58, v[42:43], off
	global_load_dword v59, v[50:51], off
	global_load_dword v60, v[52:53], off
	global_load_dwordx2 v[32:33], v[44:45], off offset:1536
	global_load_dwordx2 v[34:35], v[46:47], off offset:1536
	global_load_dwordx2 v[38:39], v[48:49], off offset:1536
	global_load_dwordx4 v[0:3], v[30:31], off
	v_lshl_add_u64 v[30:31], v[30:31], 0, s[22:23]
	s_waitcnt vmcnt(4)
;     __device__ __forceinline__ unsigned a(const pg8::Unit& u) const { return (unsigned)u.pm * (256u * K * 2u); }
;     __device__ __forceinline__ unsigned a(const pg8::Unit& u) const { return (unsigned)u.pm * (256u * K * 2u); }
;     __device__ __forceinline__ unsigned a(const pg8::Unit& u) const { return (unsigned)u.pm * (256u * K * 2u); }
;     __device__ __forceinline__ unsigned a(const pg8::Unit& u) const { return (unsigned)u.pm * (256u * K * 2u); }
;     __device__ __forceinline__ unsigned a(const pg8::Unit& u) const { return (unsigned)u.pm * (256u * K * 2u); }
; __device__ __forceinline__ void p3_combine(const Frame& F) {
;     ...
;             const int col = j * 512 + lane * 8, head = col >> 7; const size_t e = (size_t)m * EB + col;
;             const int sq = m >> 13, pos = m & (SEQ - 1);
;             const float l0 = F.LSE[((size_t)(0 * 16 + head) * NSEQ + sq) * SEQ + pos], l1 = F.LSE[((size_t)(1 * 16 + head) * NSEQ + sq) * SEQ + ((pos & 3) << 11) + (pos >> 2)],
;                         l2 = F.LSE[((size_t)(2 * 16 + head) * NSEQ + sq) * SEQ + ((pos & 15) << 9) + (pos >> 4)];
;             const float mx = fmaxf(l0, fmaxf(l1, l2));
;             float e0 = __builtin_amdgcn_exp2f(l0 - mx), e1 = __builtin_amdgcn_exp2f(l1 - mx), e2 = __builtin_amdgcn_exp2f(l2 - mx);
;             const float inv = 1.f / (e0 + e1 + e2); e0 *= inv; e1 *= inv; e2 *= inv;
;             const u32x2 a = *(const u32x2*)((const unsigned char*)F.OG0 + e), b = *(const u32x2*)((const unsigned char*)F.OG1 + e), c = *(const u32x2*)((const unsigned char*)F.OG2 + e);
;             const u32x4 z = *(const u32x4*)(F.ZB + e);
;             const unsigned aw[2] = {a.x, a.y}, bw[2] = {b.x, b.y}, cw[2] = {c.x, c.y}, zw[4] = {z.x, z.y, z.z, z.w};
;             float ov[8];
;     ...
;             P3_PAIR(0, 0, false); P3_PAIR(1, 0, true); P3_PAIR(2, 1, false); P3_PAIR(3, 1, true);
;     ...
;             int lo8 = 0, hi8 = 0;
;             lo8 = __builtin_amdgcn_cvt_pk_fp8_f32(ov[0], ov[1], lo8, false); lo8 = __builtin_amdgcn_cvt_pk_fp8_f32(ov[2], ov[3], lo8, true);
;             hi8 = __builtin_amdgcn_cvt_pk_fp8_f32(ov[4], ov[5], hi8, false); hi8 = __builtin_amdgcn_cvt_pk_fp8_f32(ov[6], ov[7], hi8, true);
;             *(u32x2*)(F.OBZ8 + e) = (u32x2){(unsigned)lo8, (unsigned)hi8};
	v_max3_f32 v61, v58, v59, v60
	s_waitcnt vmcnt(3)
	v_cvt_pk_f32_fp8_e32 v[42:43], v32
	v_cvt_pk_f32_fp8_sdwa v[48:49], v32 src0_sel:WORD_1
	s_waitcnt vmcnt(1)
	v_cvt_pk_f32_fp8_e32 v[46:47], v38
	s_waitcnt vmcnt(0)
	v_lshlrev_b32_e32 v66, 16, v2
	v_and_b32_e32 v67, 0xffff0000, v2
	v_lshlrev_b32_e32 v68, 16, v3
	v_and_b32_e32 v69, 0xffff0000, v3
	v_sub_f32_e32 v2, v58, v61
	v_sub_f32_e32 v3, v59, v61
	v_lshlrev_b32_e32 v62, 16, v0
	v_and_b32_e32 v63, 0xffff0000, v0
	v_lshlrev_b32_e32 v64, 16, v1
	v_and_b32_e32 v65, 0xffff0000, v1
	v_cvt_pk_f32_fp8_e32 v[0:1], v33
	v_cvt_pk_f32_fp8_sdwa v[32:33], v33 src0_sel:WORD_1
	v_sub_f32_e32 v58, v60, v61
	v_exp_f32_e32 v2, v2
	v_exp_f32_e32 v59, v3
	v_exp_f32_e32 v3, v58
	v_cvt_pk_f32_fp8_sdwa v[52:53], v38 src0_sel:WORD_1
	v_cvt_pk_f32_fp8_e32 v[56:57], v39
	v_cvt_pk_f32_fp8_sdwa v[38:39], v39 src0_sel:WORD_1
	v_mov_b32_e32 v60, v48
	v_mov_b32_e32 v48, v0
	v_mov_b32_e32 v0, v32
	v_add_f32_e32 v32, v2, v59
	v_add_f32_e32 v32, v3, v32
	v_mov_b32_e32 v61, v52
	v_mov_b32_e32 v52, v49
	v_mov_b32_e32 v49, v56
	v_mov_b32_e32 v56, v1
	v_mov_b32_e32 v1, v38
	v_mov_b32_e32 v38, v33
	v_div_scale_f32 v33, s[56:57], v32, v32, 1.0
	v_rcp_f32_e32 v71, v33
	v_div_scale_f32 v70, vcc, 1.0, v32, 1.0
	v_cvt_pk_f32_fp8_e32 v[44:45], v34
	v_fma_f32 v72, -v33, v71, 1.0
	v_fmac_f32_e32 v71, v72, v71
	v_mul_f32_e32 v72, v70, v71
	v_fma_f32 v73, -v33, v72, v70
	v_fmac_f32_e32 v72, v73, v71
	v_fma_f32 v33, -v33, v72, v70
	v_div_fmas_f32 v33, v33, v71, v72
	v_cvt_pk_f32_fp8_sdwa v[50:51], v34 src0_sel:WORD_1
	v_cvt_pk_f32_fp8_e32 v[54:55], v35
	v_cvt_pk_f32_fp8_sdwa v[34:35], v35 src0_sel:WORD_1
	v_div_fixup_f32 v32, v33, v32, 1.0
	v_pk_mul_f32 v[2:3], v[2:3], v[32:33] op_sel_hi:[1,0]
	v_mov_b32_e32 v58, v46
	v_mul_f32_e32 v70, v59, v32
	v_pk_mov_b32 v[32:33], v[2:3], v[42:43] op_sel:[1,0]
	v_mov_b32_e32 v59, v2
	v_mov_b32_e32 v42, v3
	v_pk_mov_b32 v[46:47], v[46:47], v[2:3] op_sel:[1,0]
	v_pk_mul_f32 v[60:61], v[2:3], v[60:61]
	v_pk_mul_f32 v[52:53], v[2:3], v[52:53]
	v_pk_mul_f32 v[48:49], v[2:3], v[48:49]
	v_pk_mul_f32 v[56:57], v[2:3], v[56:57]
	v_pk_mul_f32 v[0:1], v[2:3], v[0:1]
	v_pk_mul_f32 v[2:3], v[2:3], v[38:39]
	v_pk_mul_f32 v[32:33], v[32:33], v[58:59]
	v_pk_mul_f32 v[38:39], v[42:43], v[46:47]
	v_fma_f32 v42, v70, v50, v60
	v_fma_f32 v43, v70, v51, v52
	v_fma_f32 v46, v70, v54, v48
	v_fma_f32 v47, v70, v55, v56
	v_fma_f32 v0, v70, v34, v0
	v_fma_f32 v2, v70, v35, v2
	v_fma_f32 v33, v44, v70, v33
	v_fma_f32 v34, v45, v70, v39
	v_add_f32_e32 v35, v42, v61
	v_add_f32_e32 v39, v43, v53
	v_add_f32_e32 v42, v46, v49
	v_add_f32_e32 v43, v47, v57
	v_add_f32_e32 v0, v0, v1
	v_add_f32_e32 v1, v2, v3
	v_add_f32_e32 v2, v32, v33
	v_add_f32_e32 v3, v38, v34
	v_mul_f32_e32 v32, v35, v64
	v_mul_f32_e32 v34, v42, v66
	v_mul_f32_e32 v35, v43, v67
	v_mul_f32_e32 v2, v2, v62
	v_mul_f32_e32 v3, v3, v63
	v_add_f32_e32 v34, v34, v34
	v_add_f32_e32 v35, v35, v35
	v_add_f32_e32 v2, v2, v2
	v_add_f32_e32 v3, v3, v3
	v_cvt_pk_fp8_f32 v41, v34, v35
	v_cvt_pk_fp8_f32 v40, v2, v3
	v_mul_f32_e32 v33, v39, v65
	v_mul_f32_e32 v0, v0, v68
	v_mul_f32_e32 v1, v1, v69
	v_add_f32_e32 v32, v32, v32
	v_add_f32_e32 v33, v33, v33
	v_add_f32_e32 v0, v0, v0
	v_add_f32_e32 v1, v1, v1
	v_cvt_pk_fp8_f32 v41, v0, v1 op_sel:[0,0,1]
	v_cvt_pk_fp8_f32 v40, v32, v33 op_sel:[0,0,1]
	global_store_dwordx2 v[36:37], v[40:41], off offset:1536
	s_cbranch_scc1 .LBB0_365
